# retention chunk loop: counted vmcnt(2) at loop top so O stores need not be acked before next chunk staging
# speedup vs baseline: 1.0143x; 1.0057x over previous
.LBB0_437:
	s_or_b64 exec, exec, s[38:39]
	s_and_b32 s36, s13, 0x3000
	s_mov_b32 s37, s57
	v_lshl_add_u64 v[2:3], v[80:81], 0, s[36:37]
	s_and_b32 s36, s11, 0xffffffc0
	s_and_b32 s15, s12, 7
	s_ashr_i32 s37, s36, 31
	s_lshl_b32 s38, s15, 10
	s_lshl_b64 s[36:37], s[36:37], 1
	s_add_u32 s36, s36, s38
	v_lshlrev_b64 v[2:3], 13, v[2:3]
	s_addc_u32 s37, s37, 0
	s_lshl_b32 s38, s13, 13
	v_or_b32_e32 v2, v90, v2
	s_and_b32 s38, s38, 0x6000000
	v_lshl_add_u64 v[112:113], s[36:37], 0, v[2:3]
	s_add_u32 s36, s36, s38
	s_addc_u32 s37, s37, 0
	v_lshl_add_u64 v[114:115], s[36:37], 0, v[92:93]
	s_lshl_b32 s36, s13, 12
	s_and_b32 s36, s36, 0x3000000
	s_mov_b32 s37, s57
	v_lshl_add_u64 v[2:3], v[94:95], 0, s[36:37]
	v_lshl_or_b32 v4, s15, 9, v175
	v_mov_b32_e32 v5, v187
	s_and_b32 s40, s14, 7
	v_lshl_add_u64 v[116:117], v[2:3], 0, v[4:5]
	v_lshl_add_u64 v[2:3], v[96:97], 0, s[36:37]
	v_cvt_f32_ubyte0_e32 v1, s40
	v_lshl_add_u64 v[118:119], v[2:3], 0, v[4:5]
	v_lshl_add_u64 v[2:3], v[98:99], 0, s[36:37]
	v_sub_f32_e32 v1, 0xc0a00000, v1
	v_lshl_add_u64 v[120:121], v[2:3], 0, v[4:5]
	v_lshl_add_u64 v[2:3], v[100:101], 0, s[36:37]
	v_cmp_gt_f32_e64 s[36:37], s52, v1
	v_lshl_add_u64 v[122:123], v[2:3], 0, v[4:5]
	v_mov_b32_e32 v103, v187
	v_cndmask_b32_e64 v2, 0, v234, s[36:37]
	v_add_f32_e32 v1, v1, v2
	v_exp_f32_e32 v1, v1
	s_and_b64 s[36:37], s[36:37], exec
	s_cselect_b32 s15, 0xffffffc0, 0
	v_mov_b32_e32 v2, 0x42000000
	v_ldexp_f32 v1, v1, s15
	v_sub_f32_e32 v1, 1.0, v1
	s_mov_b32 s15, 0x800000
	v_cmp_gt_f32_e64 s[36:37], s15, v1
	s_and_b64 s[38:39], s[36:37], exec
	s_cselect_b32 s15, 32, 0
	v_ldexp_f32 v1, v1, s15
	v_log_f32_e32 v1, v1
	v_cndmask_b32_e64 v2, 0, v2, s[36:37]
	s_mov_b32 s39, s57
	v_sub_f32_e32 v1, v1, v2
	v_mul_f32_e32 v2, 0x42800000, v1
	v_cmp_gt_f32_e64 s[36:37], s52, v2
	v_mul_f32_e32 v38, v1, v91
	s_nop 0
	v_cndmask_b32_e64 v2, 0, v234, s[36:37]
	v_fmac_f32_e32 v2, 0x42800000, v1
	v_exp_f32_e32 v2, v2
	s_and_b64 s[36:37], s[36:37], exec
	s_cselect_b32 s15, 0xffffffc0, 0
	s_lshl_b32 s36, s40, 10
	v_ldexp_f32 v104, v2, s15
	s_lshl_b32 s15, s14, 9
	s_and_b32 s38, s15, 0x3000
	s_lshl_b32 s15, s40, 9
	v_lshl_add_u64 v[26:27], s[38:39], 0, v[88:89]
	v_lshl_add_u64 v[2:3], s[38:39], 0, v[82:83]
	v_or_b32_e32 v28, s15, v175
	v_lshl_add_u64 v[10:11], s[38:39], 0, v[84:85]
	v_lshl_add_u64 v[18:19], s[38:39], 0, v[86:87]
	v_lshlrev_b64 v[26:27], 12, v[26:27]
	v_lshlrev_b64 v[6:7], 12, v[2:3]
	v_lshlrev_b64 v[14:15], 12, v[10:11]
	v_lshlrev_b64 v[22:23], 12, v[18:19]
	v_or_b32_e32 v26, v26, v28
	v_or_b32_e32 v6, v6, v28
	v_or_b32_e32 v14, v14, v28
	v_or_b32_e32 v22, v22, v28
	v_lshl_add_u64 v[28:29], s[16:17], 0, v[26:27]
	v_lshl_add_u64 v[26:27], s[18:19], 0, v[26:27]
	global_load_dwordx4 v[30:33], v[28:29], off
	global_load_dwordx4 v[34:37], v[26:27], off
	v_lshl_add_u64 v[26:27], s[38:39], 0, v[78:79]
	v_lshlrev_b64 v[26:27], 13, v[26:27]
	v_lshl_add_u64 v[26:27], s[20:21], 0, v[26:27]
	s_mov_b32 s37, s57
	v_lshl_add_u64 v[26:27], v[26:27], 0, s[36:37]
	s_lshl_b32 s36, s14, 1
	s_and_b32 s40, s36, 0xffffffc0
	s_ashr_i32 s41, s40, 31
	v_lshl_add_u64 v[26:27], s[40:41], 1, v[26:27]
	v_lshl_add_u64 v[2:3], s[16:17], 0, v[6:7]
	v_lshl_add_u64 v[6:7], s[18:19], 0, v[6:7]
	v_lshl_add_u64 v[10:11], s[16:17], 0, v[14:15]
	v_lshl_add_u64 v[14:15], s[18:19], 0, v[14:15]
	v_lshl_add_u64 v[18:19], s[16:17], 0, v[22:23]
	v_lshl_add_u64 v[22:23], s[18:19], 0, v[22:23]
	v_lshl_add_u64 v[26:27], v[26:27], 0, v[102:103]
	v_cmp_gt_f32_e64 s[36:37], s52, v38
	global_load_dwordx4 v[2:5], v[2:3], off
	v_mov_b32_e32 v106, v104
	global_load_dwordx4 v[6:9], v[6:7], off
	v_cndmask_b32_e64 v38, 0, v234, s[36:37]
	global_load_dwordx4 v[10:13], v[10:11], off
	v_fmac_f32_e32 v38, v1, v91
	global_load_dwordx4 v[14:17], v[14:15], off
	v_exp_f32_e32 v38, v38
	global_load_dwordx4 v[18:21], v[18:19], off
	v_cndmask_b32_e64 v39, 0, v236, s[36:37]
	global_load_dwordx4 v[22:25], v[22:23], off
	v_ldexp_f32 v124, v38, v39
	global_load_dwordx4 v[26:29], v[26:27], off
	v_mul_f32_e32 v38, v1, v128
	v_cmp_gt_f32_e64 s[36:37], s52, v38
	v_mov_b32_e32 v107, v104
	v_mov_b32_e32 v125, v124
	v_cndmask_b32_e64 v38, 0, v234, s[36:37]
	v_fmac_f32_e32 v38, v1, v128
	v_exp_f32_e32 v38, v38
	v_cndmask_b32_e64 v39, 0, v236, s[36:37]
	s_mov_b32 s39, 63
	v_ldexp_f32 v108, v38, v39
	v_mul_f32_e32 v38, v1, v129
	v_cmp_gt_f32_e64 s[36:37], s52, v38
	v_mov_b32_e32 v109, v108
	v_mov_b32_e32 v110, v108
	v_cndmask_b32_e64 v38, 0, v234, s[36:37]
	v_fmac_f32_e32 v38, v1, v129
	v_exp_f32_e32 v38, v38
	v_cndmask_b32_e64 v39, 0, v236, s[36:37]
	v_mov_b32_e32 v111, v108
	v_ldexp_f32 v103, v38, v39
	v_mul_f32_e32 v38, v1, v130
	v_cmp_gt_f32_e64 s[36:37], s52, v38
	s_nop 1
	v_cndmask_b32_e64 v38, 0, v234, s[36:37]
	v_fmac_f32_e32 v38, v1, v130
	v_exp_f32_e32 v38, v38
	v_cndmask_b32_e64 v39, 0, v236, s[36:37]
	v_ldexp_f32 v198, v38, v39
	v_mul_f32_e32 v38, v1, v132
	v_cmp_gt_f32_e64 s[36:37], s52, v38
	s_nop 1
	v_cndmask_b32_e64 v38, 0, v234, s[36:37]
	v_fmac_f32_e32 v38, v1, v132
	v_exp_f32_e32 v38, v38
	v_cndmask_b32_e64 v39, 0, v236, s[36:37]
	v_ldexp_f32 v199, v38, v39
	v_mul_f32_e32 v38, v1, v133
	v_cmp_gt_f32_e64 s[36:37], s52, v38
	s_nop 1
	v_cndmask_b32_e64 v38, 0, v234, s[36:37]
	v_fmac_f32_e32 v38, v1, v133
	v_exp_f32_e32 v38, v38
	v_cndmask_b32_e64 v39, 0, v236, s[36:37]
	v_ldexp_f32 v200, v38, v39
	v_mul_f32_e32 v38, v1, v135
	v_cmp_gt_f32_e64 s[36:37], s52, v38
	s_nop 1
	v_cndmask_b32_e64 v38, 0, v234, s[36:37]
	v_fmac_f32_e32 v38, v1, v135
	v_exp_f32_e32 v38, v38
	v_cndmask_b32_e64 v39, 0, v236, s[36:37]
	v_ldexp_f32 v201, v38, v39
	v_mul_f32_e32 v38, v1, v136
	v_cmp_gt_f32_e64 s[36:37], s52, v38
	s_nop 1
	v_cndmask_b32_e64 v38, 0, v234, s[36:37]
	v_fmac_f32_e32 v38, v1, v136
	v_exp_f32_e32 v38, v38
	v_cndmask_b32_e64 v39, 0, v236, s[36:37]
	v_ldexp_f32 v202, v38, v39
	v_mul_f32_e32 v38, v1, v138
	v_cmp_gt_f32_e64 s[36:37], s52, v38
	s_nop 1
	v_cndmask_b32_e64 v38, 0, v234, s[36:37]
	v_fmac_f32_e32 v38, v1, v138
	v_exp_f32_e32 v38, v38
	v_cndmask_b32_e64 v39, 0, v236, s[36:37]
	v_ldexp_f32 v203, v38, v39
	v_mul_f32_e32 v38, v1, v139
	v_cmp_gt_f32_e64 s[36:37], s52, v38
	s_nop 1
	v_cndmask_b32_e64 v38, 0, v234, s[36:37]
	v_fmac_f32_e32 v38, v1, v139
	v_exp_f32_e32 v1, v38
	v_cndmask_b32_e64 v38, 0, v236, s[36:37]
	v_ldexp_f32 v204, v1, v38
	v_mov_b32_e32 v38, 0
	v_mov_b32_e32 v39, v38
	v_mov_b32_e32 v40, v38
	v_mov_b32_e32 v41, v38
	v_mov_b32_e32 v42, v38
	v_mov_b32_e32 v43, v38
	v_mov_b32_e32 v44, v38
	v_mov_b32_e32 v45, v38
	v_mov_b32_e32 v46, v38
	v_mov_b32_e32 v47, v38
	v_mov_b32_e32 v48, v38
	v_mov_b32_e32 v49, v38
	v_mov_b32_e32 v54, v38
	v_mov_b32_e32 v55, v38
	v_mov_b32_e32 v56, v38
	v_mov_b32_e32 v57, v38
	v_mov_b32_e32 v50, v38
	v_mov_b32_e32 v51, v38
	v_mov_b32_e32 v52, v38
	v_mov_b32_e32 v53, v38
	v_mov_b32_e32 v58, v38
	v_mov_b32_e32 v59, v38
	v_mov_b32_e32 v60, v38
	v_mov_b32_e32 v61, v38
	v_mov_b32_e32 v62, v38
	v_mov_b32_e32 v63, v38
	v_mov_b32_e32 v64, v38
	v_mov_b32_e32 v65, v38
	v_mov_b32_e32 v66, v38
	v_mov_b32_e32 v67, v38
	v_mov_b32_e32 v68, v38
	v_mov_b32_e32 v69, v38
	s_waitcnt vmcnt(0)
.LBB0_438:
	s_waitcnt vmcnt(2)
	ds_write_b128 v176, v[2:5]
	ds_write_b128 v176, v[6:9] offset:33792
	ds_write_b128 v177, v[10:13]
	ds_write_b128 v177, v[14:17] offset:33792
	ds_write_b128 v178, v[18:21]
	ds_write_b128 v178, v[22:25] offset:33792
	ds_write_b128 v179, v[30:33]
	ds_write_b128 v179, v[34:37] offset:33792
	ds_write_b128 v180, v[26:29]
	v_lshlrev_b32_e32 v2, 16, v26
	v_and_b32_e32 v3, 0xffff0000, v26
	v_lshlrev_b32_e32 v4, 16, v27
	v_and_b32_e32 v5, 0xffff0000, v27
	v_pk_mul_f32 v[2:3], v[124:125], v[2:3]
	v_pk_mul_f32 v[4:5], v[124:125], v[4:5]
	v_cvt_pk_bf16_f32 v2, v2, v3
	v_cvt_pk_bf16_f32 v3, v4, v5
	v_lshlrev_b32_e32 v4, 16, v28
	v_and_b32_e32 v5, 0xffff0000, v28
	v_lshlrev_b32_e32 v6, 16, v29
	v_and_b32_e32 v7, 0xffff0000, v29
	v_pk_mul_f32 v[4:5], v[124:125], v[4:5]
	v_pk_mul_f32 v[6:7], v[124:125], v[6:7]
	v_cvt_pk_bf16_f32 v4, v4, v5
	v_cvt_pk_bf16_f32 v5, v6, v7
	v_lshl_add_u64 v[6:7], s[78:79], 0, v[122:123]
	ds_write_b128 v181, v[2:5]
	v_add_co_u32_e64 v2, s[36:37], s27, v6
	v_lshl_add_u64 v[14:15], s[78:79], 0, v[120:121]
	s_nop 0
	v_addc_co_u32_e64 v3, s[36:37], 0, v7, s[36:37]
	v_add_co_u32_e64 v6, s[36:37], s28, v6
	v_lshl_add_u64 v[22:23], s[78:79], 0, v[118:119]
	s_nop 0
	v_addc_co_u32_e64 v7, s[36:37], 0, v7, s[36:37]
	v_add_co_u32_e64 v10, s[36:37], s27, v14
	v_lshl_add_u64 v[26:27], s[78:79], 0, v[116:117]
	s_nop 0
	v_addc_co_u32_e64 v11, s[36:37], 0, v15, s[36:37]
	v_add_co_u32_e64 v14, s[36:37], s28, v14
	s_waitcnt lgkmcnt(0)
	s_nop 0
	v_addc_co_u32_e64 v15, s[36:37], 0, v15, s[36:37]
	v_add_co_u32_e64 v18, s[36:37], s27, v22
	s_barrier
	s_nop 0
	v_addc_co_u32_e64 v19, s[36:37], 0, v23, s[36:37]
	v_add_co_u32_e64 v22, s[36:37], s28, v22
	s_nop 1
	v_addc_co_u32_e64 v23, s[36:37], 0, v23, s[36:37]
	v_add_co_u32_e64 v28, s[36:37], s27, v26
	global_load_dwordx4 v[2:5], v[2:3], off
	s_nop 0
	v_addc_co_u32_e64 v29, s[36:37], 0, v27, s[36:37]
	v_add_co_u32_e64 v26, s[36:37], s28, v26
	global_load_dwordx4 v[30:33], v[28:29], off
	s_nop 0
	v_addc_co_u32_e64 v27, s[36:37], 0, v27, s[36:37]
	global_load_dwordx4 v[34:37], v[26:27], off
	v_lshl_add_u64 v[26:27], s[78:79], 0, v[114:115]
	global_load_dwordx4 v[6:9], v[6:7], off
	v_add_u32_e32 v205, v131, v127
	global_load_dwordx4 v[10:13], v[10:11], off
	s_mov_b32 s36, 0x59a00000
	global_load_dwordx4 v[14:17], v[14:15], off
	v_mov_b32_e32 v105, v104
	global_load_dwordx4 v[18:21], v[18:19], off
	v_pk_mul_f32 v[68:69], v[104:105], v[68:69]
	global_load_dwordx4 v[22:25], v[22:23], off
	v_pk_mul_f32 v[66:67], v[106:107], v[66:67]
	global_load_dwordx4 v[26:29], v[26:27], off
	ds_read_b128 v[70:73], v182
	ds_read_b128 v[74:77], v183 offset:33792
	ds_read_b128 v[188:191], v183 offset:42240
	s_waitcnt lgkmcnt(1)
	v_mfma_f32_16x16x32_bf16 v[74:77], v[70:73], v[74:77], 0
	v_mul_f32_e64 v64, v104, v64
	v_mul_f32_e64 v65, v105, v65
	v_pk_mul_f32 v[62:63], v[106:107], v[62:63]
	v_pk_mul_f32 v[60:61], v[104:105], v[60:61]
	s_waitcnt lgkmcnt(0)
	v_mfma_f32_16x16x32_bf16 v[70:73], v[70:73], v[188:191], 0
	ds_read_b128 v[188:191], v182 offset:64
	ds_read_b128 v[192:195], v183 offset:33856
	ds_read_b128 v[206:209], v183 offset:42304
	v_pk_mul_f32 v[58:59], v[106:107], v[58:59]
	v_pk_mul_f32 v[48:49], v[104:105], v[48:49]
	s_waitcnt lgkmcnt(1)
	v_mfma_f32_16x16x32_bf16 v[74:77], v[188:191], v[192:195], v[74:77]
	v_mul_f32_e64 v46, v106, v46
	v_mul_f32_e64 v47, v107, v47
	v_pk_mul_f32 v[44:45], v[104:105], v[44:45]
	v_pk_mul_f32 v[42:43], v[106:107], v[42:43]
	s_waitcnt lgkmcnt(0)
	v_mfma_f32_16x16x32_bf16 v[70:73], v[188:191], v[206:209], v[70:73]
	ds_read_b128 v[188:191], v182 offset:128
	ds_read_b128 v[192:195], v183 offset:33920
	ds_read_b128 v[206:209], v183 offset:42368
	v_pk_mul_f32 v[40:41], v[104:105], v[40:41]
	v_pk_mul_f32 v[38:39], v[106:107], v[38:39]
	s_waitcnt lgkmcnt(1)
	v_mfma_f32_16x16x32_bf16 v[74:77], v[188:191], v[192:195], v[74:77]
	s_add_i32 s39, s39, -1
	v_lshl_add_u64 v[114:115], v[114:115], 0, s[34:35]
	v_lshl_add_u64 v[116:117], v[116:117], 0, s[86:87]
	s_waitcnt lgkmcnt(0)
	v_mfma_f32_16x16x32_bf16 v[70:73], v[188:191], v[206:209], v[70:73]
	ds_read_b128 v[188:191], v182 offset:192
	ds_read_b128 v[192:195], v183 offset:33984
	ds_read_b128 v[206:209], v183 offset:42432
	v_lshl_add_u64 v[118:119], v[118:119], 0, s[86:87]
	v_lshl_add_u64 v[120:121], v[120:121], 0, s[86:87]
	s_waitcnt lgkmcnt(1)
	v_mfma_f32_16x16x32_bf16 v[74:77], v[188:191], v[192:195], v[74:77]
	v_lshl_add_u64 v[122:123], v[122:123], 0, s[86:87]
	s_cmp_lg_u32 s39, 0
	s_waitcnt lgkmcnt(0)
	v_mfma_f32_16x16x32_bf16 v[70:73], v[188:191], v[206:209], v[70:73]
	ds_read_b128 v[188:191], v182 offset:256
	ds_read_b128 v[192:195], v183 offset:34048
	ds_read_b128 v[206:209], v183 offset:42496
	s_waitcnt lgkmcnt(1)
	v_mfma_f32_16x16x32_bf16 v[74:77], v[188:191], v[192:195], v[74:77]
	s_waitcnt lgkmcnt(0)
	v_mfma_f32_16x16x32_bf16 v[70:73], v[188:191], v[206:209], v[70:73]
	ds_read_b128 v[188:191], v182 offset:320
	ds_read_b128 v[192:195], v183 offset:34112
	ds_read_b128 v[206:209], v183 offset:42560
	s_waitcnt lgkmcnt(1)
	v_mfma_f32_16x16x32_bf16 v[74:77], v[188:191], v[192:195], v[74:77]
	s_waitcnt lgkmcnt(0)
	v_mfma_f32_16x16x32_bf16 v[70:73], v[188:191], v[206:209], v[70:73]
	ds_read_b128 v[188:191], v182 offset:384
	ds_read_b128 v[192:195], v183 offset:34176
	ds_read_b128 v[206:209], v183 offset:42624
	s_waitcnt lgkmcnt(1)
	v_mfma_f32_16x16x32_bf16 v[74:77], v[188:191], v[192:195], v[74:77]
	s_waitcnt lgkmcnt(0)
	v_mfma_f32_16x16x32_bf16 v[70:73], v[188:191], v[206:209], v[70:73]
	ds_read_b128 v[188:191], v182 offset:448
	ds_read_b128 v[192:195], v183 offset:34240
	ds_read_b128 v[206:209], v183 offset:42688
	s_waitcnt lgkmcnt(1)
	v_mfma_f32_16x16x32_bf16 v[74:77], v[188:191], v[192:195], v[74:77]
	s_waitcnt lgkmcnt(0)
	v_mfma_f32_16x16x32_bf16 v[70:73], v[188:191], v[206:209], v[70:73]
	s_nop 5
	v_mul_f32_e32 v1, v103, v74
	v_cvt_pk_bf16_f32 v1, v1, s0
	v_add_u32_e32 v74, v131, v126
	ds_write_b16 v74, v1
	v_add_u32_e32 v206, v134, v127
	v_mul_f32_e32 v1, v198, v70
	v_cvt_pk_bf16_f32 v1, v1, s0
	ds_write_b16 v205, v1
	v_mul_f32_e32 v1, v199, v75
	v_cvt_pk_bf16_f32 v1, v1, s0
	v_add_u32_e32 v75, v134, v126
	ds_write_b16 v75, v1
	v_mul_f32_e32 v1, v200, v71
	v_cvt_pk_bf16_f32 v1, v1, s0
	ds_write_b16 v206, v1
	v_mul_f32_e32 v1, v201, v76
	v_cvt_pk_bf16_f32 v1, v1, s0
	v_add_u32_e32 v76, v137, v126
	ds_write_b16 v76, v1
	v_mul_f32_e32 v1, v202, v72
	v_cvt_pk_bf16_f32 v1, v1, s0
	v_add_u32_e32 v207, v137, v127
	ds_write_b16 v207, v1
	v_mul_f32_e32 v1, v203, v77
	v_cvt_pk_bf16_f32 v1, v1, s0
	v_add_u32_e32 v77, v140, v126
	ds_write_b16 v77, v1
	v_mul_f32_e32 v1, v204, v73
	v_cvt_pk_bf16_f32 v1, v1, s0
	v_add_u32_e32 v208, v140, v127
	ds_write_b16 v208, v1
	s_waitcnt lgkmcnt(0)
	s_barrier
	ds_read_b128 v[70:73], v182
	ds_read_b128 v[188:191], v184
	ds_read_b128 v[192:195], v184 offset:8448
	s_waitcnt lgkmcnt(1)
	v_mfma_f32_16x16x32_bf16 v[188:191], v[188:191], v[70:73], 0
	s_waitcnt lgkmcnt(0)
	v_mfma_f32_16x16x32_bf16 v[70:73], v[192:195], v[70:73], 0
	ds_read_b128 v[192:195], v182 offset:64
	ds_read_b128 v[210:213], v184 offset:64
	ds_read_b128 v[214:217], v184 offset:8512
	s_waitcnt lgkmcnt(1)
	v_mfma_f32_16x16x32_bf16 v[188:191], v[210:213], v[192:195], v[188:191]
	s_waitcnt lgkmcnt(0)
	v_mfma_f32_16x16x32_bf16 v[70:73], v[214:217], v[192:195], v[70:73]
	ds_read_b128 v[192:195], v182 offset:128
	ds_read_b128 v[210:213], v184 offset:128
	ds_read_b128 v[214:217], v184 offset:8576
	s_waitcnt lgkmcnt(1)
	v_mfma_f32_16x16x32_bf16 v[188:191], v[210:213], v[192:195], v[188:191]
	s_waitcnt lgkmcnt(0)
	v_mfma_f32_16x16x32_bf16 v[70:73], v[214:217], v[192:195], v[70:73]
	ds_read_b128 v[192:195], v182 offset:192
	ds_read_b128 v[210:213], v184 offset:192
	ds_read_b128 v[214:217], v184 offset:8640
	s_waitcnt lgkmcnt(1)
	v_mfma_f32_16x16x32_bf16 v[188:191], v[210:213], v[192:195], v[188:191]
	s_waitcnt lgkmcnt(0)
	v_mfma_f32_16x16x32_bf16 v[70:73], v[214:217], v[192:195], v[70:73]
	ds_read_b128 v[192:195], v182 offset:256
	ds_read_b128 v[210:213], v184 offset:256
	ds_read_b128 v[214:217], v184 offset:8704
	s_waitcnt lgkmcnt(1)
	v_mfma_f32_16x16x32_bf16 v[188:191], v[210:213], v[192:195], v[188:191]
	s_waitcnt lgkmcnt(0)
	v_mfma_f32_16x16x32_bf16 v[70:73], v[214:217], v[192:195], v[70:73]
	ds_read_b128 v[192:195], v182 offset:320
	ds_read_b128 v[210:213], v184 offset:320
	ds_read_b128 v[214:217], v184 offset:8768
	s_waitcnt lgkmcnt(1)
	v_mfma_f32_16x16x32_bf16 v[188:191], v[210:213], v[192:195], v[188:191]
	s_waitcnt lgkmcnt(0)
	v_mfma_f32_16x16x32_bf16 v[70:73], v[214:217], v[192:195], v[70:73]
	ds_read_b128 v[192:195], v182 offset:384
	ds_read_b128 v[210:213], v184 offset:384
	ds_read_b128 v[214:217], v184 offset:8832
	s_waitcnt lgkmcnt(1)
	v_mfma_f32_16x16x32_bf16 v[188:191], v[210:213], v[192:195], v[188:191]
	s_waitcnt lgkmcnt(0)
	v_mfma_f32_16x16x32_bf16 v[70:73], v[214:217], v[192:195], v[70:73]
	ds_read_b128 v[192:195], v182 offset:448
	ds_read_b128 v[210:213], v184 offset:448
	ds_read_b128 v[214:217], v184 offset:8896
	s_waitcnt lgkmcnt(1)
	v_mfma_f32_16x16x32_bf16 v[188:191], v[210:213], v[192:195], v[188:191]
	s_waitcnt lgkmcnt(0)
	v_mfma_f32_16x16x32_bf16 v[70:73], v[214:217], v[192:195], v[70:73]
	ds_read_b128 v[192:195], v185
	s_nop 4
	v_pk_mul_f32 v[190:191], v[110:111], v[190:191]
	v_pk_mul_f32 v[188:189], v[108:109], v[188:189]
	ds_read_b64_tr_b16 v[214:215], v141
	ds_read_b64_tr_b16 v[216:217], v142
	ds_read_b64_tr_b16 v[210:211], v143
	ds_read_b64_tr_b16 v[212:213], v144
	s_waitcnt lgkmcnt(0)
	s_waitcnt lgkmcnt(0)
	s_nop 0
	v_mfma_f32_16x16x32_bf16 v[188:191], v[214:217], v[192:195], v[188:191]
	v_mul_f32_e64 v72, v110, v72
	v_mul_f32_e64 v73, v111, v73
	v_pk_mul_f32 v[70:71], v[108:109], v[70:71]
	s_nop 1
	v_mfma_f32_16x16x32_bf16 v[70:73], v[210:213], v[192:195], v[70:73]
	ds_read_b128 v[192:195], v185 offset:64
	ds_read_b64_tr_b16 v[214:215], v145
	ds_read_b64_tr_b16 v[216:217], v146
	ds_read_b64_tr_b16 v[210:211], v147
	ds_read_b64_tr_b16 v[212:213], v148
	s_waitcnt lgkmcnt(0)
	s_waitcnt lgkmcnt(0)
	v_mfma_f32_16x16x32_bf16 v[188:191], v[214:217], v[192:195], v[188:191]
	v_mfma_f32_16x16x32_bf16 v[192:195], v[210:213], v[192:195], v[70:73]
	s_nop 6
	v_cvt_pk_bf16_f32 v70, v188, v189
	v_lshl_add_u64 v[188:189], s[78:79], 0, v[112:113]
	v_add_co_u32_e64 v188, s[36:37], s36, v188
	v_cvt_pk_bf16_f32 v71, v190, v191
	s_nop 0
	v_addc_co_u32_e64 v189, s[36:37], 0, v189, s[36:37]
	v_cvt_pk_bf16_f32 v72, v192, v193
	v_cvt_pk_bf16_f32 v73, v194, v195
	global_store_dwordx2 v[188:189], v[70:71], off
	global_store_dwordx2 v[188:189], v[72:73], off offset:32
	v_pk_mul_f32 v[72:73], v[104:105], v[52:53]
	v_pk_mul_f32 v[70:71], v[106:107], v[50:51]
	v_pk_mul_f32 v[52:53], v[104:105], v[56:57]
	v_pk_mul_f32 v[50:51], v[106:107], v[54:55]
	ds_read_b64_tr_b16 v[188:189], v149
	ds_read_b64_tr_b16 v[190:191], v151
	ds_read_b64_tr_b16 v[54:55], v152
	ds_read_b64_tr_b16 v[56:57], v153
	s_waitcnt lgkmcnt(0)
	ds_read_b64_tr_b16 v[210:211], v150
	ds_read_b64_tr_b16 v[212:213], v154
	ds_read_b64_tr_b16 v[192:193], v155
	ds_read_b64_tr_b16 v[194:195], v156
	s_waitcnt lgkmcnt(0)
	ds_read_b64_tr_b16 v[218:219], v157
	ds_read_b64_tr_b16 v[220:221], v158
	ds_read_b64_tr_b16 v[214:215], v159
	ds_read_b64_tr_b16 v[216:217], v160
	s_waitcnt lgkmcnt(0)
	v_lshl_add_u64 v[112:113], v[112:113], 0, s[34:35]
	v_mfma_f32_16x16x32_bf16 v[66:69], v[188:191], v[210:213], v[66:69]
	v_mfma_f32_16x16x32_bf16 v[62:65], v[188:191], v[192:195], v[62:65]
	v_mfma_f32_16x16x32_bf16 v[58:61], v[188:191], v[218:221], v[58:61]
	v_mfma_f32_16x16x32_bf16 v[70:73], v[188:191], v[214:217], v[70:73]
	v_mfma_f32_16x16x32_bf16 v[188:191], v[54:57], v[210:213], v[50:53]
	v_mfma_f32_16x16x32_bf16 v[46:49], v[54:57], v[192:195], v[46:49]
	ds_read_b64_tr_b16 v[50:51], v161
	ds_read_b64_tr_b16 v[52:53], v163
	ds_read_b64_tr_b16 v[192:193], v164
	ds_read_b64_tr_b16 v[194:195], v165
	s_waitcnt lgkmcnt(0)
	v_mfma_f32_16x16x32_bf16 v[42:45], v[54:57], v[218:221], v[42:45]
	v_mfma_f32_16x16x32_bf16 v[38:41], v[54:57], v[214:217], v[38:41]
	ds_read_b64_tr_b16 v[54:55], v162
	ds_read_b64_tr_b16 v[56:57], v166
	ds_read_b64_tr_b16 v[210:211], v167
	ds_read_b64_tr_b16 v[212:213], v168
	s_waitcnt lgkmcnt(0)
	ds_read_b64_tr_b16 v[218:219], v169
	ds_read_b64_tr_b16 v[220:221], v170
	ds_read_b64_tr_b16 v[214:215], v171
	ds_read_b64_tr_b16 v[216:217], v172
	s_waitcnt lgkmcnt(0)
	s_nop 0
	v_mfma_f32_16x16x32_bf16 v[66:69], v[50:53], v[54:57], v[66:69]
	s_barrier
	v_mfma_f32_16x16x32_bf16 v[62:65], v[50:53], v[210:213], v[62:65]
	v_mfma_f32_16x16x32_bf16 v[58:61], v[50:53], v[218:221], v[58:61]
	v_mfma_f32_16x16x32_bf16 v[50:53], v[50:53], v[214:217], v[70:73]
	v_mfma_f32_16x16x32_bf16 v[54:57], v[192:195], v[54:57], v[188:191]
	s_nop 2
	v_cvt_pk_bf16_f32 v70, v66, v67
	v_cvt_pk_bf16_f32 v71, v68, v69
	ds_write_b64 v196, v[70:71]
	v_mfma_f32_16x16x32_bf16 v[46:49], v[192:195], v[210:213], v[46:49]
	v_cvt_pk_bf16_f32 v70, v62, v63
	v_cvt_pk_bf16_f32 v71, v64, v65
	ds_write_b64 v196, v[70:71] offset:8448
	v_mfma_f32_16x16x32_bf16 v[42:45], v[192:195], v[218:221], v[42:45]
	v_cvt_pk_bf16_f32 v70, v58, v59
	v_cvt_pk_bf16_f32 v71, v60, v61
	ds_write_b64 v196, v[70:71] offset:16896
	v_mfma_f32_16x16x32_bf16 v[38:41], v[192:195], v[214:217], v[38:41]
	v_cvt_pk_bf16_f32 v70, v50, v51
	v_cvt_pk_bf16_f32 v71, v52, v53
	ds_write_b64 v196, v[70:71] offset:25344
	v_cvt_pk_bf16_f32 v70, v54, v55
	v_cvt_pk_bf16_f32 v71, v56, v57
	ds_write_b64 v197, v[70:71]
	v_cvt_pk_bf16_f32 v70, v46, v47
	v_cvt_pk_bf16_f32 v71, v48, v49
	ds_write_b64 v197, v[70:71] offset:8448
	v_cvt_pk_bf16_f32 v70, v42, v43
	v_cvt_pk_bf16_f32 v71, v44, v45
	ds_write_b64 v197, v[70:71] offset:16896
	v_cvt_pk_bf16_f32 v70, v38, v39
	v_cvt_pk_bf16_f32 v71, v40, v41
	ds_write_b64 v197, v[70:71] offset:25344
	s_cbranch_scc1 .LBB0_438
	s_waitcnt vmcnt(10)
	ds_write_b128 v176, v[2:5]
	s_waitcnt vmcnt(7)
	ds_write_b128 v176, v[6:9] offset:33792
	s_waitcnt vmcnt(6)
	ds_write_b128 v177, v[10:13]
	s_waitcnt vmcnt(5)
	ds_write_b128 v177, v[14:17] offset:33792
	s_waitcnt vmcnt(4)
	ds_write_b128 v178, v[18:21]
	s_waitcnt vmcnt(3)
	ds_write_b128 v178, v[22:25] offset:33792
	ds_write_b128 v179, v[30:33]
	ds_write_b128 v179, v[34:37] offset:33792
	s_waitcnt vmcnt(2)
	ds_write_b128 v180, v[26:29]
	v_lshlrev_b32_e32 v2, 16, v26
	v_and_b32_e32 v3, 0xffff0000, v26
	v_lshlrev_b32_e32 v4, 16, v27
	v_and_b32_e32 v5, 0xffff0000, v27
	v_pk_mul_f32 v[2:3], v[124:125], v[2:3]
	v_pk_mul_f32 v[4:5], v[124:125], v[4:5]
	v_cvt_pk_bf16_f32 v2, v2, v3
	v_cvt_pk_bf16_f32 v3, v4, v5
	v_lshlrev_b32_e32 v4, 16, v28
	v_and_b32_e32 v5, 0xffff0000, v28
	v_lshlrev_b32_e32 v6, 16, v29
	v_and_b32_e32 v7, 0xffff0000, v29
	v_pk_mul_f32 v[4:5], v[124:125], v[4:5]
	v_pk_mul_f32 v[6:7], v[124:125], v[6:7]
	v_cvt_pk_bf16_f32 v4, v4, v5
	v_cvt_pk_bf16_f32 v5, v6, v7
	ds_write_b128 v181, v[2:5]
	s_waitcnt lgkmcnt(0)
	s_barrier
	ds_read_b128 v[2:5], v182
	ds_read_b128 v[6:9], v183 offset:33792
	ds_read_b128 v[10:13], v182 offset:64
	ds_read_b128 v[14:17], v183 offset:33856
	s_waitcnt lgkmcnt(2)
	v_mfma_f32_16x16x32_bf16 v[6:9], v[2:5], v[6:9], 0
	ds_read_b128 v[18:21], v183 offset:42240
	ds_read_b128 v[22:25], v183 offset:42304
	s_lshl_b32 s15, s15, 1
	s_add_u32 s15, s7, s15
	s_waitcnt lgkmcnt(2)
	v_mfma_f32_16x16x32_bf16 v[6:9], v[10:13], v[14:17], v[6:9]
	ds_read_b128 v[14:17], v182 offset:128
	s_addc_u32 s39, s10, 0
	s_lshl_b64 s[36:37], s[40:41], 1
	s_waitcnt lgkmcnt(2)
	v_mfma_f32_16x16x32_bf16 v[2:5], v[2:5], v[18:21], 0
	s_add_u32 s36, s15, s36
	s_addc_u32 s37, s39, s37
	v_pk_mul_f32 v[30:31], v[104:105], v[60:61]
	s_waitcnt lgkmcnt(1)
	v_mfma_f32_16x16x32_bf16 v[2:5], v[10:13], v[22:25], v[2:5]
	ds_read_b128 v[10:13], v183 offset:33920
	ds_read_b128 v[18:21], v182 offset:192
	ds_read_b128 v[22:25], v183 offset:33984
	v_pk_mul_f32 v[52:53], v[104:105], v[52:53]
	v_pk_mul_f32 v[50:51], v[106:107], v[50:51]
	s_waitcnt lgkmcnt(2)
	v_mfma_f32_16x16x32_bf16 v[6:9], v[14:17], v[10:13], v[6:9]
	ds_read_b128 v[10:13], v183 offset:42368
	ds_read_b128 v[26:29], v183 offset:42432
	v_pk_mul_f32 v[48:49], v[104:105], v[48:49]
	v_pk_mul_f32 v[46:47], v[106:107], v[46:47]
	s_waitcnt lgkmcnt(1)
	v_mfma_f32_16x16x32_bf16 v[2:5], v[14:17], v[10:13], v[2:5]
	ds_read_b128 v[10:13], v182 offset:256
	v_pk_mul_f32 v[44:45], v[104:105], v[44:45]
	v_pk_mul_f32 v[42:43], v[106:107], v[42:43]
	v_mfma_f32_16x16x32_bf16 v[6:9], v[18:21], v[22:25], v[6:9]
	v_mul_f32_e64 v40, v104, v40
	v_mul_f32_e64 v41, v105, v41
	v_pk_mul_f32 v[38:39], v[106:107], v[38:39]
	s_add_i32 s14, s14, s85
	s_waitcnt lgkmcnt(1)
	v_mfma_f32_16x16x32_bf16 v[2:5], v[18:21], v[26:29], v[2:5]
	ds_read_b128 v[14:17], v183 offset:34048
	ds_read_b128 v[18:21], v182 offset:320
	ds_read_b128 v[22:25], v183 offset:34112
	s_add_i32 s13, s13, s50
	s_add_i32 s12, s12, s85
	s_waitcnt lgkmcnt(2)
	v_mfma_f32_16x16x32_bf16 v[6:9], v[10:13], v[14:17], v[6:9]
	ds_read_b128 v[14:17], v183 offset:42496
	ds_read_b128 v[26:29], v183 offset:42560
	s_add_i32 s11, s11, s51
	s_waitcnt lgkmcnt(1)
	v_mfma_f32_16x16x32_bf16 v[2:5], v[10:13], v[14:17], v[2:5]
	ds_read_b128 v[10:13], v182 offset:384
	v_mfma_f32_16x16x32_bf16 v[6:9], v[18:21], v[22:25], v[6:9]
	s_waitcnt lgkmcnt(1)
	v_mfma_f32_16x16x32_bf16 v[2:5], v[18:21], v[26:29], v[2:5]
	ds_read_b128 v[14:17], v183 offset:34176
	ds_read_b128 v[18:21], v182 offset:448
	ds_read_b128 v[22:25], v183 offset:34240
	s_waitcnt lgkmcnt(2)
	v_mfma_f32_16x16x32_bf16 v[6:9], v[10:13], v[14:17], v[6:9]
	ds_read_b128 v[14:17], v183 offset:42624
	ds_read_b128 v[26:29], v183 offset:42688
	s_waitcnt lgkmcnt(1)
	v_mfma_f32_16x16x32_bf16 v[2:5], v[10:13], v[14:17], v[2:5]
	v_mfma_f32_16x16x32_bf16 v[6:9], v[18:21], v[22:25], v[6:9]
	s_waitcnt lgkmcnt(0)
	v_mfma_f32_16x16x32_bf16 v[2:5], v[18:21], v[26:29], v[2:5]
	s_nop 5
	v_mul_f32_e32 v1, v103, v6
	v_cvt_pk_bf16_f32 v1, v1, s0
	ds_write_b16 v74, v1
	v_mul_f32_e32 v1, v198, v2
	v_cvt_pk_bf16_f32 v1, v1, s0
	ds_write_b16 v205, v1
	v_mul_f32_e32 v1, v199, v7
	v_cvt_pk_bf16_f32 v1, v1, s0
	ds_write_b16 v75, v1
	v_mul_f32_e32 v1, v200, v3
	v_cvt_pk_bf16_f32 v1, v1, s0
	ds_write_b16 v206, v1
	v_mul_f32_e32 v1, v201, v8
	v_cvt_pk_bf16_f32 v1, v1, s0
	ds_write_b16 v76, v1
	v_mul_f32_e32 v1, v202, v4
	v_cvt_pk_bf16_f32 v1, v1, s0
	ds_write_b16 v207, v1
	v_mul_f32_e32 v1, v203, v9
	v_cvt_pk_bf16_f32 v1, v1, s0
	ds_write_b16 v77, v1
	v_mul_f32_e32 v1, v204, v5
	v_cvt_pk_bf16_f32 v1, v1, s0
	ds_write_b16 v208, v1
	s_waitcnt lgkmcnt(0)
	s_barrier
	ds_read_b128 v[2:5], v184
	ds_read_b128 v[6:9], v182
	ds_read_b128 v[10:13], v182 offset:64
	ds_read_b128 v[14:17], v184 offset:64
	s_waitcnt lgkmcnt(2)
	v_mfma_f32_16x16x32_bf16 v[2:5], v[2:5], v[6:9], 0
	ds_read_b128 v[18:21], v184 offset:8448
	ds_read_b128 v[22:25], v184 offset:8512
	s_waitcnt lgkmcnt(2)
	v_mfma_f32_16x16x32_bf16 v[2:5], v[14:17], v[10:13], v[2:5]
	ds_read_b128 v[14:17], v184 offset:128
	s_waitcnt lgkmcnt(2)
	v_mfma_f32_16x16x32_bf16 v[6:9], v[18:21], v[6:9], 0
	s_waitcnt lgkmcnt(1)
	v_mfma_f32_16x16x32_bf16 v[6:9], v[22:25], v[10:13], v[6:9]
	ds_read_b128 v[10:13], v182 offset:128
	ds_read_b128 v[18:21], v182 offset:192
	ds_read_b128 v[22:25], v184 offset:192
	s_waitcnt lgkmcnt(2)
	v_mfma_f32_16x16x32_bf16 v[2:5], v[14:17], v[10:13], v[2:5]
	ds_read_b128 v[14:17], v184 offset:8576
	ds_read_b128 v[26:29], v184 offset:8640
	s_waitcnt lgkmcnt(1)
	v_mfma_f32_16x16x32_bf16 v[6:9], v[14:17], v[10:13], v[6:9]
	ds_read_b128 v[10:13], v184 offset:256
	v_mfma_f32_16x16x32_bf16 v[2:5], v[22:25], v[18:21], v[2:5]
	s_waitcnt lgkmcnt(1)
	v_mfma_f32_16x16x32_bf16 v[6:9], v[26:29], v[18:21], v[6:9]
	ds_read_b128 v[14:17], v182 offset:256
	ds_read_b128 v[18:21], v182 offset:320
	ds_read_b128 v[22:25], v184 offset:320
	s_waitcnt lgkmcnt(2)
	v_mfma_f32_16x16x32_bf16 v[2:5], v[10:13], v[14:17], v[2:5]
	ds_read_b128 v[10:13], v184 offset:8704
	ds_read_b128 v[26:29], v184 offset:8768
	s_waitcnt lgkmcnt(1)
	v_mfma_f32_16x16x32_bf16 v[6:9], v[10:13], v[14:17], v[6:9]
	ds_read_b128 v[10:13], v184 offset:384
	v_mfma_f32_16x16x32_bf16 v[2:5], v[22:25], v[18:21], v[2:5]
	s_waitcnt lgkmcnt(1)
	v_mfma_f32_16x16x32_bf16 v[6:9], v[26:29], v[18:21], v[6:9]
	ds_read_b128 v[14:17], v182 offset:384
	ds_read_b128 v[18:21], v182 offset:448
	ds_read_b128 v[22:25], v184 offset:448
	s_waitcnt lgkmcnt(2)
	v_mfma_f32_16x16x32_bf16 v[2:5], v[10:13], v[14:17], v[2:5]
	ds_read_b128 v[10:13], v184 offset:8832
	ds_read_b128 v[26:29], v184 offset:8896
	s_waitcnt lgkmcnt(1)
	v_mfma_f32_16x16x32_bf16 v[6:9], v[10:13], v[14:17], v[6:9]
	ds_read_b128 v[10:13], v185
	v_mfma_f32_16x16x32_bf16 v[2:5], v[22:25], v[18:21], v[2:5]
	s_waitcnt lgkmcnt(1)
	v_mfma_f32_16x16x32_bf16 v[6:9], v[26:29], v[18:21], v[6:9]
	ds_read_b64_tr_b16 v[18:19], v141
	ds_read_b64_tr_b16 v[20:21], v142
	ds_read_b64_tr_b16 v[14:15], v143
	ds_read_b64_tr_b16 v[16:17], v144
	s_waitcnt lgkmcnt(0)
	s_nop 5
	v_mul_f32_e64 v4, v110, v4
	v_mul_f32_e64 v5, v111, v5
	v_pk_mul_f32 v[2:3], v[108:109], v[2:3]
	v_pk_mul_f32 v[28:29], v[106:107], v[58:59]
	s_waitcnt lgkmcnt(0)
	v_mfma_f32_16x16x32_bf16 v[2:5], v[18:21], v[10:13], v[2:5]
	v_mul_f32_e64 v8, v110, v8
	v_mul_f32_e64 v9, v111, v9
	v_pk_mul_f32 v[6:7], v[108:109], v[6:7]
	s_nop 1
	v_mfma_f32_16x16x32_bf16 v[6:9], v[14:17], v[10:13], v[6:9]
	ds_read_b128 v[10:13], v185 offset:64
	ds_read_b64_tr_b16 v[18:19], v145
	ds_read_b64_tr_b16 v[20:21], v146
	ds_read_b64_tr_b16 v[14:15], v147
	ds_read_b64_tr_b16 v[16:17], v148
	s_waitcnt lgkmcnt(0)
	s_waitcnt lgkmcnt(0)
	v_mfma_f32_16x16x32_bf16 v[2:5], v[18:21], v[10:13], v[2:5]
	v_lshl_add_u64 v[18:19], s[36:37], 0, v[186:187]
	s_or_b32 s36, s38, 0xfc0
	s_mov_b32 s37, s57
	v_mfma_f32_16x16x32_bf16 v[6:9], v[14:17], v[10:13], v[6:9]
	v_lshl_add_u64 v[10:11], v[80:81], 0, s[36:37]
	v_lshl_add_u64 v[18:19], v[18:19], 0, s[56:57]
	s_nop 1
	v_cvt_pk_bf16_f32 v2, v2, v3
	v_cvt_pk_bf16_f32 v3, v4, v5
	s_cmpk_lt_i32 s14, 0x100
	s_nop 0
	v_cvt_pk_bf16_f32 v4, v6, v7
	v_lshlrev_b64 v[6:7], 13, v[10:11]
	v_lshl_add_u64 v[6:7], v[18:19], 0, v[6:7]
	v_cvt_pk_bf16_f32 v5, v8, v9
	global_store_dwordx2 v[6:7], v[2:3], off
	global_store_dwordx2 v[6:7], v[4:5], off offset:32
	v_pk_mul_f32 v[4:5], v[104:105], v[68:69]
	v_pk_mul_f32 v[2:3], v[106:107], v[66:67]
	ds_read_b64_tr_b16 v[12:13], v149
	ds_read_b64_tr_b16 v[14:15], v151
	ds_read_b64_tr_b16 v[8:9], v152
	ds_read_b64_tr_b16 v[10:11], v153
	s_waitcnt lgkmcnt(0)
	v_pk_mul_f32 v[6:7], v[104:105], v[64:65]
	ds_read_b64_tr_b16 v[20:21], v150
	ds_read_b64_tr_b16 v[22:23], v154
	ds_read_b64_tr_b16 v[16:17], v155
	ds_read_b64_tr_b16 v[18:19], v156
	s_waitcnt lgkmcnt(0)
	ds_read_b64_tr_b16 v[58:59], v157
	ds_read_b64_tr_b16 v[60:61], v158
	ds_read_b64_tr_b16 v[32:33], v159
	ds_read_b64_tr_b16 v[34:35], v160
	s_waitcnt lgkmcnt(0)
	s_nop 0
	v_mfma_f32_16x16x32_bf16 v[24:27], v[12:15], v[20:23], v[2:5]
	s_nop 2
	v_mul_f32_e64 v4, v106, v62
	v_mul_f32_e64 v5, v107, v63
	v_mfma_f32_16x16x32_bf16 v[28:31], v[12:15], v[58:61], v[28:31]
	s_nop 0
	v_mfma_f32_16x16x32_bf16 v[2:5], v[12:15], v[16:19], v[4:7]
	v_mfma_f32_16x16x32_bf16 v[12:15], v[12:15], v[32:35], v[50:53]
	s_nop 2
	v_mul_f32_e64 v52, v104, v56
	v_mul_f32_e64 v53, v105, v57
	v_pk_mul_f32 v[50:51], v[106:107], v[54:55]
	v_mfma_f32_16x16x32_bf16 v[16:19], v[8:11], v[16:19], v[46:49]
	s_nop 0
	v_mfma_f32_16x16x32_bf16 v[20:23], v[8:11], v[20:23], v[50:53]
	v_mfma_f32_16x16x32_bf16 v[42:45], v[8:11], v[58:61], v[42:45]
	v_mfma_f32_16x16x32_bf16 v[6:9], v[8:11], v[32:35], v[38:41]
	ds_read_b64_tr_b16 v[36:37], v161
	ds_read_b64_tr_b16 v[38:39], v163
	ds_read_b64_tr_b16 v[32:33], v164
	ds_read_b64_tr_b16 v[34:35], v165
	s_waitcnt lgkmcnt(0)
	ds_read_b64_tr_b16 v[50:51], v162
	ds_read_b64_tr_b16 v[52:53], v166
	ds_read_b64_tr_b16 v[46:47], v167
	ds_read_b64_tr_b16 v[48:49], v168
	s_waitcnt lgkmcnt(0)
	ds_read_b64_tr_b16 v[58:59], v169
	ds_read_b64_tr_b16 v[60:61], v170
	ds_read_b64_tr_b16 v[54:55], v171
	ds_read_b64_tr_b16 v[56:57], v172
	s_waitcnt lgkmcnt(0)
	s_nop 0
	v_mfma_f32_16x16x32_bf16 v[2:5], v[36:39], v[46:49], v[2:5]
	s_barrier
	v_mfma_f32_16x16x32_bf16 v[28:31], v[36:39], v[58:61], v[28:31]
	v_mfma_f32_16x16x32_bf16 v[10:13], v[36:39], v[54:57], v[12:15]
	s_nop 4
	v_cvt_pk_bf16_f32 v2, v2, v3
	v_cvt_pk_bf16_f32 v3, v4, v5
	ds_write_b64 v196, v[2:3] offset:8448
	v_mfma_f32_16x16x32_bf16 v[20:23], v[32:35], v[50:53], v[20:23]
	v_cvt_pk_bf16_f32 v2, v28, v29
	v_cvt_pk_bf16_f32 v3, v30, v31
	ds_write_b64 v196, v[2:3] offset:16896
	v_mfma_f32_16x16x32_bf16 v[14:17], v[32:35], v[46:49], v[16:19]
	v_cvt_pk_bf16_f32 v2, v10, v11
	v_cvt_pk_bf16_f32 v3, v12, v13
	ds_write_b64 v196, v[2:3] offset:25344
	v_mfma_f32_16x16x32_bf16 v[24:27], v[36:39], v[50:53], v[24:27]
	v_cvt_pk_bf16_f32 v2, v20, v21
	v_cvt_pk_bf16_f32 v3, v22, v23
	ds_write_b64 v197, v[2:3]
	v_mfma_f32_16x16x32_bf16 v[36:39], v[32:35], v[58:61], v[42:45]
	v_cvt_pk_bf16_f32 v2, v14, v15
	v_cvt_pk_bf16_f32 v3, v16, v17
	ds_write_b64 v197, v[2:3] offset:8448
	v_mfma_f32_16x16x32_bf16 v[6:9], v[32:35], v[54:57], v[6:9]
	v_cvt_pk_bf16_f32 v18, v24, v25
	s_nop 2
	v_cvt_pk_bf16_f32 v2, v36, v37
	v_cvt_pk_bf16_f32 v3, v38, v39
	v_cvt_pk_bf16_f32 v19, v26, v27
	ds_write_b64 v197, v[2:3] offset:16896
	v_cvt_pk_bf16_f32 v2, v6, v7
	v_cvt_pk_bf16_f32 v3, v8, v9
	ds_write_b64 v196, v[18:19]
	ds_write_b64 v197, v[2:3] offset:25344
	s_waitcnt lgkmcnt(0)
	s_barrier
	s_cbranch_scc1 .LBB0_434
